# version 69 plus ph_s0t (phase-0 retention-state transpose) with the 32 strided loads of a thread's four iterations issued before the conversions and stores (G==256 path)
# baseline (speedup 1.0000x reference)
.LBB0_42:
	s_or_b64 exec, exec, s[0:1]
	s_mov_b32 s0, 0x80000
	v_readlane_b32 s97, v255, 47
	v_cmp_gt_i32_e32 vcc, s0, v1
	s_and_saveexec_b64 s[4:5], vcc
	s_cbranch_execz .LBB0_45
	v_readlane_b32 s0, v255, 43
	v_readlane_b32 s12, v255, 41
	v_lshlrev_b32_e32 v2, 3, v0
	v_readlane_b32 s1, v255, 44
	v_readlane_b32 s13, v255, 42
	s_lshl_b32 s3, s33, 9
	v_lshl_or_b32 v4, s2, 12, v2
	s_lshl_b32 s8, s33, 12
	s_mov_b64 s[6:7], 0
	s_mov_b32 s9, 0x40000
	v_mov_b32_e32 v5, s63
	v_mov_b32_e32 v6, s61
	v_mov_b32_e32 v7, s62
	v_mov_b32_e32 v8, s60
	s_movk_i32 s10, 0x1f00
	v_mov_b32_e32 v3, 0
	s_movk_i32 s11, 0x1000
	v_mov_b32_e32 v9, s1
	v_mov_b32_e32 v10, s13
	v_mov_b32_e32 v11, s0
	v_mov_b32_e32 v12, s12
	s_movk_i32 s24, 0xff
	v_mov_b32_e32 v13, 0x1f00
	s_mov_b32 s25, 0x7ffff
	s_cmp_lg_u32 s33, 0x100
	s_cbranch_scc1 .LBB0_44
	v_lshrrev_b32_e32 v18, 5, v1
	v_and_b32_e32 v19, 0xf8, v4
	v_cmp_gt_u32_e32 vcc, s9, v1
	v_and_or_b32 v2, v18, s10, v19
	v_bfe_u32 v16, v1, 5, 8
	v_cndmask_b32_e32 v15, v5, v6, vcc
	v_cndmask_b32_e32 v14, v7, v8, vcc
	v_lshlrev_b32_e32 v2, 10, v2
	v_lshl_add_u64 v[14:15], v[14:15], 0, v[2:3]
	v_lshlrev_b32_e32 v2, 2, v16
	v_lshl_add_u64 v[14:15], v[14:15], 0, v[2:3]
	v_add_co_u32_e64 v16, s[0:1], s11, v14
	v_bitop3_b32 v2, v18, s24, v13 bitop3:0xe0
	s_nop 0
	v_addc_co_u32_e64 v17, s[0:1], 0, v15, s[0:1]
	global_load_dword v88, v[14:15], off
	global_load_dword v89, v[14:15], off offset:1024
	global_load_dword v90, v[14:15], off offset:2048
	global_load_dword v91, v[14:15], off offset:3072
	global_load_dword v92, v[16:17], off
	global_load_dword v93, v[16:17], off offset:1024
	global_load_dword v94, v[16:17], off offset:2048
	s_nop 0
	global_load_dword v95, v[16:17], off offset:3072
	v_add_u32_e32 v1, s3, v1
	v_cndmask_b32_e32 v15, v9, v10, vcc
	v_cndmask_b32_e32 v14, v11, v12, vcc
	v_lshlrev_b32_e32 v2, 9, v2
	v_cmp_lt_i32_e32 vcc, s25, v1
	v_lshl_add_u64 v[14:15], v[14:15], 0, v[2:3]
	v_lshlrev_b32_e32 v2, 1, v19
	v_add_u32_e32 v4, s8, v4
	s_or_b64 s[6:7], vcc, s[6:7]
	v_lshl_add_u64 v[120:121], v[14:15], 0, v[2:3]
	v_lshrrev_b32_e32 v18, 5, v1
	v_and_b32_e32 v19, 0xf8, v4
	v_cmp_gt_u32_e32 vcc, s9, v1
	v_and_or_b32 v2, v18, s10, v19
	v_bfe_u32 v16, v1, 5, 8
	v_cndmask_b32_e32 v15, v5, v6, vcc
	v_cndmask_b32_e32 v14, v7, v8, vcc
	v_lshlrev_b32_e32 v2, 10, v2
	v_lshl_add_u64 v[14:15], v[14:15], 0, v[2:3]
	v_lshlrev_b32_e32 v2, 2, v16
	v_lshl_add_u64 v[14:15], v[14:15], 0, v[2:3]
	v_add_co_u32_e64 v16, s[0:1], s11, v14
	v_bitop3_b32 v2, v18, s24, v13 bitop3:0xe0
	s_nop 0
	v_addc_co_u32_e64 v17, s[0:1], 0, v15, s[0:1]
	global_load_dword v96, v[14:15], off
	global_load_dword v97, v[14:15], off offset:1024
	global_load_dword v98, v[14:15], off offset:2048
	global_load_dword v99, v[14:15], off offset:3072
	global_load_dword v100, v[16:17], off
	global_load_dword v101, v[16:17], off offset:1024
	global_load_dword v102, v[16:17], off offset:2048
	s_nop 0
	global_load_dword v103, v[16:17], off offset:3072
	v_add_u32_e32 v1, s3, v1
	v_cndmask_b32_e32 v15, v9, v10, vcc
	v_cndmask_b32_e32 v14, v11, v12, vcc
	v_lshlrev_b32_e32 v2, 9, v2
	v_cmp_lt_i32_e32 vcc, s25, v1
	v_lshl_add_u64 v[14:15], v[14:15], 0, v[2:3]
	v_lshlrev_b32_e32 v2, 1, v19
	v_add_u32_e32 v4, s8, v4
	s_or_b64 s[6:7], vcc, s[6:7]
	v_lshl_add_u64 v[122:123], v[14:15], 0, v[2:3]
	v_lshrrev_b32_e32 v18, 5, v1
	v_and_b32_e32 v19, 0xf8, v4
	v_cmp_gt_u32_e32 vcc, s9, v1
	v_and_or_b32 v2, v18, s10, v19
	v_bfe_u32 v16, v1, 5, 8
	v_cndmask_b32_e32 v15, v5, v6, vcc
	v_cndmask_b32_e32 v14, v7, v8, vcc
	v_lshlrev_b32_e32 v2, 10, v2
	v_lshl_add_u64 v[14:15], v[14:15], 0, v[2:3]
	v_lshlrev_b32_e32 v2, 2, v16
	v_lshl_add_u64 v[14:15], v[14:15], 0, v[2:3]
	v_add_co_u32_e64 v16, s[0:1], s11, v14
	v_bitop3_b32 v2, v18, s24, v13 bitop3:0xe0
	s_nop 0
	v_addc_co_u32_e64 v17, s[0:1], 0, v15, s[0:1]
	global_load_dword v104, v[14:15], off
	global_load_dword v105, v[14:15], off offset:1024
	global_load_dword v106, v[14:15], off offset:2048
	global_load_dword v107, v[14:15], off offset:3072
	global_load_dword v108, v[16:17], off
	global_load_dword v109, v[16:17], off offset:1024
	global_load_dword v110, v[16:17], off offset:2048
	s_nop 0
	global_load_dword v111, v[16:17], off offset:3072
	v_add_u32_e32 v1, s3, v1
	v_cndmask_b32_e32 v15, v9, v10, vcc
	v_cndmask_b32_e32 v14, v11, v12, vcc
	v_lshlrev_b32_e32 v2, 9, v2
	v_cmp_lt_i32_e32 vcc, s25, v1
	v_lshl_add_u64 v[14:15], v[14:15], 0, v[2:3]
	v_lshlrev_b32_e32 v2, 1, v19
	v_add_u32_e32 v4, s8, v4
	s_or_b64 s[6:7], vcc, s[6:7]
	v_lshl_add_u64 v[124:125], v[14:15], 0, v[2:3]
	v_lshrrev_b32_e32 v18, 5, v1
	v_and_b32_e32 v19, 0xf8, v4
	v_cmp_gt_u32_e32 vcc, s9, v1
	v_and_or_b32 v2, v18, s10, v19
	v_bfe_u32 v16, v1, 5, 8
	v_cndmask_b32_e32 v15, v5, v6, vcc
	v_cndmask_b32_e32 v14, v7, v8, vcc
	v_lshlrev_b32_e32 v2, 10, v2
	v_lshl_add_u64 v[14:15], v[14:15], 0, v[2:3]
	v_lshlrev_b32_e32 v2, 2, v16
	v_lshl_add_u64 v[14:15], v[14:15], 0, v[2:3]
	v_add_co_u32_e64 v16, s[0:1], s11, v14
	v_bitop3_b32 v2, v18, s24, v13 bitop3:0xe0
	s_nop 0
	v_addc_co_u32_e64 v17, s[0:1], 0, v15, s[0:1]
	global_load_dword v112, v[14:15], off
	global_load_dword v113, v[14:15], off offset:1024
	global_load_dword v114, v[14:15], off offset:2048
	global_load_dword v115, v[14:15], off offset:3072
	global_load_dword v116, v[16:17], off
	global_load_dword v117, v[16:17], off offset:1024
	global_load_dword v118, v[16:17], off offset:2048
	s_nop 0
	global_load_dword v119, v[16:17], off offset:3072
	v_add_u32_e32 v1, s3, v1
	v_cndmask_b32_e32 v15, v9, v10, vcc
	v_cndmask_b32_e32 v14, v11, v12, vcc
	v_lshlrev_b32_e32 v2, 9, v2
	v_cmp_lt_i32_e32 vcc, s25, v1
	v_lshl_add_u64 v[14:15], v[14:15], 0, v[2:3]
	v_lshlrev_b32_e32 v2, 1, v19
	v_add_u32_e32 v4, s8, v4
	s_or_b64 s[6:7], vcc, s[6:7]
	v_lshl_add_u64 v[126:127], v[14:15], 0, v[2:3]
	s_waitcnt vmcnt(24)
	v_cvt_pk_bf16_f32 v130, v88, v89
	v_cvt_pk_bf16_f32 v131, v90, v91
	v_cvt_pk_bf16_f32 v132, v92, v93
	v_cvt_pk_bf16_f32 v133, v94, v95
	global_store_dwordx4 v[120:121], v[130:133], off
	s_waitcnt vmcnt(17)
	v_cvt_pk_bf16_f32 v134, v96, v97
	v_cvt_pk_bf16_f32 v135, v98, v99
	v_cvt_pk_bf16_f32 v136, v100, v101
	v_cvt_pk_bf16_f32 v137, v102, v103
	global_store_dwordx4 v[122:123], v[134:137], off
	s_waitcnt vmcnt(10)
	v_cvt_pk_bf16_f32 v138, v104, v105
	v_cvt_pk_bf16_f32 v139, v106, v107
	v_cvt_pk_bf16_f32 v140, v108, v109
	v_cvt_pk_bf16_f32 v141, v110, v111
	global_store_dwordx4 v[124:125], v[138:141], off
	s_waitcnt vmcnt(3)
	v_cvt_pk_bf16_f32 v142, v112, v113
	v_cvt_pk_bf16_f32 v143, v114, v115
	v_cvt_pk_bf16_f32 v144, v116, v117
	v_cvt_pk_bf16_f32 v145, v118, v119
	global_store_dwordx4 v[126:127], v[142:145], off
	s_branch .LBB0_45
